# P4 prompt attention: O stores widened with v_permlane32_swap pairs (4 dwordx4 instead of 8 dwordx2 per wave item), on top of P3/P7/P2 store widening
# baseline (speedup 1.0000x reference)
; __device__ __forceinline__ unsigned cvt_pk_bf16(float lo, float hi) { unsigned r; asm volatile("v_cvt_pk_bf16_f32 %0, %1, %2" : "=v"(r) : "v"(lo), "v"(hi)); return r; }
; __device__ __forceinline__ void phase_attention(KParams P, LAS unsigned char* lds, const int wave_sg) {
;     ...
;         lsum += __shfl_xor(lsum, 32);
;         const float inv = __builtin_amdgcn_rcpf(lsum);
;         const int sq = (blk * 128 + 32 * w + r32) * dil + rres; const size_t row = (size_t)b * 2048 + sq;
;         bf16* dst = (hq < 8) ? OA + row * 768 + hq * 64 : OB3 + ((size_t)g * MP + row) * 256 + slot * 64;
; #pragma unroll
;         for (int dh = 0; dh < 2; ++dh)
; #pragma unroll
;             for (int c = 0; c < 4; ++c) { u32x2 wv; wv.x = cvt_pk_bf16(o[dh][4 * c] * inv, o[dh][4 * c + 1] * inv); wv.y = cvt_pk_bf16(o[dh][4 * c + 2] * inv, o[dh][4 * c + 3] * inv);
;                 *(u32x2*)(dst + 32 * dh + 8 * c + 4 * hi) = wv; }
;         if (hq >= 8 && hi == 0) LSE3[((size_t)g * MP + row) * 4 + slot] = (mx + __builtin_amdgcn_logf(lsum)) * LN2;
.LBB0_827:
	s_waitcnt lgkmcnt(0)
	v_add_f32_e32 v37, v37, v38
	v_rcp_f32_e32 v38, v37
	v_lshl_add_u64 v[34:35], v[34:35], 0, v[144:145]
	v_lshl_add_u64 v[34:35], v[34:35], 0, v[144:145]
	s_cmp_gt_i32 s82, 7
	s_cselect_b64 s[0:1], -1, 0
	v_mul_f32_e32 v0, v0, v38
	v_mul_f32_e32 v1, v1, v38
	v_cvt_pk_bf16_f32 v0, v0, v1
	v_mul_f32_e32 v1, v2, v38
	v_mul_f32_e32 v2, v3, v38
	v_cvt_pk_bf16_f32 v1, v1, v2
	v_mul_f32_e32 v2, v4, v38
	v_mul_f32_e32 v3, v5, v38
	v_cvt_pk_bf16_f32 v2, v2, v3
	v_mul_f32_e32 v3, v6, v38
	v_mul_f32_e32 v4, v7, v38
	v_cvt_pk_bf16_f32 v3, v3, v4
	s_nop 1
	v_permlane32_swap_b32_e32 v0, v2
	v_permlane32_swap_b32_e32 v1, v3
	global_store_dwordx4 v[34:35], v[0:3], off
	v_mul_f32_e32 v4, v8, v38
	v_mul_f32_e32 v5, v9, v38
	v_cvt_pk_bf16_f32 v4, v4, v5
	v_mul_f32_e32 v5, v10, v38
	v_mul_f32_e32 v6, v11, v38
	v_cvt_pk_bf16_f32 v5, v5, v6
	v_mul_f32_e32 v6, v12, v38
	v_mul_f32_e32 v7, v13, v38
	v_cvt_pk_bf16_f32 v6, v6, v7
	v_mul_f32_e32 v7, v14, v38
	v_mul_f32_e32 v8, v15, v38
	v_cvt_pk_bf16_f32 v7, v7, v8
	s_nop 1
	v_permlane32_swap_b32_e32 v4, v6
	v_permlane32_swap_b32_e32 v5, v7
	global_store_dwordx4 v[34:35], v[4:7], off offset:32
	v_mul_f32_e32 v8, v16, v38
	v_mul_f32_e32 v9, v17, v38
	v_cvt_pk_bf16_f32 v8, v8, v9
	v_mul_f32_e32 v9, v18, v38
	v_mul_f32_e32 v10, v19, v38
	v_cvt_pk_bf16_f32 v9, v9, v10
	v_mul_f32_e32 v10, v20, v38
	v_mul_f32_e32 v11, v21, v38
	v_cvt_pk_bf16_f32 v10, v10, v11
	v_mul_f32_e32 v11, v22, v38
	v_mul_f32_e32 v12, v23, v38
	v_cvt_pk_bf16_f32 v11, v11, v12
	s_nop 1
	v_permlane32_swap_b32_e32 v8, v10
	v_permlane32_swap_b32_e32 v9, v11
	global_store_dwordx4 v[34:35], v[8:11], off offset:64
	v_mul_f32_e32 v12, v24, v38
	v_mul_f32_e32 v13, v25, v38
	v_cvt_pk_bf16_f32 v12, v12, v13
	v_mul_f32_e32 v13, v26, v38
	v_mul_f32_e32 v14, v27, v38
	v_cvt_pk_bf16_f32 v13, v13, v14
	v_mul_f32_e32 v14, v28, v38
	v_mul_f32_e32 v15, v29, v38
	v_cvt_pk_bf16_f32 v14, v14, v15
	v_mul_f32_e32 v15, v30, v38
	v_mul_f32_e32 v16, v31, v38
	v_cvt_pk_bf16_f32 v15, v15, v16
	s_nop 1
	v_permlane32_swap_b32_e32 v12, v14
	v_permlane32_swap_b32_e32 v13, v15
	global_store_dwordx4 v[34:35], v[12:15], off offset:96
	s_and_b64 s[76:77], s[0:1], s[8:9]
	s_and_saveexec_b64 s[0:1], s[76:77]
	s_cbranch_execz .LBB0_809
	v_log_f32_e32 v0, v37
	v_readlane_b32 s10, v255, 32
	v_readlane_b32 s11, v255, 33
	s_lshl_b32 s4, s94, 2
	v_add_f32_e32 v0, v36, v0
	v_mul_f32_e32 v2, 0x3f317218, v0
	v_mad_i64_i32 v[0:1], s[76:77], s83, v245, v[32:33]
	v_lshl_add_u64 v[0:1], v[0:1], 4, s[10:11]
	v_lshl_add_u64 v[0:1], v[0:1], 0, s[4:5]
	global_store_dword v[0:1], v2, off
	s_branch .LBB0_809
